# merge: K-step 1 and 2 global loads issued in the per-group prologue together with step 0 (latencies overlap)
# speedup vs baseline: 1.0227x; 1.0041x over previous
.LBB0_1009:
	s_lshl_b64 s[38:39], s[36:37], 1
	s_add_u32 s18, s46, s38
	s_addc_u32 s19, s47, s39
	v_mov_b32_e32 v34, v192
	v_mov_b64_e32 v[2:3], s[18:19]
	v_ashrrev_i32_e32 v30, 3, v34
	v_lshlrev_b32_e32 v0, 4, v34
	s_lshl_b32 s8, s66, 20
	v_mad_i64_i32 v[2:3], s[18:19], v30, s65, v[2:3]
	v_and_b32_e32 v0, 0x70, v0
	s_add_u32 s36, s48, s8
	v_lshl_add_u64 v[2:3], v[2:3], 0, v[0:1]
	s_mov_b32 s8, 0xf8000
	v_add_co_u32_e32 v10, vcc, s8, v2
	s_mov_b32 s8, 0x1f0000
	s_nop 0
	v_addc_co_u32_e32 v11, vcc, 0, v3, vcc
	v_add_co_u32_e32 v14, vcc, s8, v2
	v_ashrrev_i32_e32 v31, 31, v30
	s_nop 0
	v_addc_co_u32_e32 v15, vcc, 0, v3, vcc
	s_mov_b32 s8, 0x2e8000
	s_addc_u32 s37, s49, 0
	v_lshlrev_b64 v[32:33], 10, v[30:31]
	global_load_dwordx4 v[6:9], v[2:3], off
	s_nop 0
	global_load_dwordx4 v[10:13], v[10:11], off
	v_add_co_u32_e32 v2, vcc, s8, v2
	v_lshl_add_u64 v[4:5], s[36:37], 0, v[32:33]
	s_nop 0
	v_addc_co_u32_e32 v3, vcc, 0, v3, vcc
	global_load_dwordx4 v[14:17], v[14:15], off
	s_nop 0
	global_load_dwordx4 v[18:21], v[2:3], off
	v_lshl_add_u64 v[2:3], v[4:5], 0, v[0:1]
	s_mov_b32 s8, 0x10000
	v_add_co_u32_e32 v4, vcc, s8, v2
	v_lshrrev_b32_e32 v31, 1, v34
	s_nop 0
	v_addc_co_u32_e32 v5, vcc, 0, v3, vcc
	global_load_dwordx4 v[22:25], v[2:3], off
	global_load_dwordx4 v[26:29], v[4:5], off
	v_and_b32_e32 v36, 15, v34
	s_mov_b32 s12, 0x7ffffc0
	v_lshrrev_b32_e32 v35, 4, v34
	v_and_b32_e32 v39, 16, v31
	v_and_or_b32 v31, v31, s12, v36
	s_mov_b32 s12, 0x7ffffe0
	v_and_b32_e32 v37, 48, v34
	v_and_b32_e32 v38, 0x4f, v34
	v_and_b32_e32 v40, 12, v35
	v_and_b32_e32 v41, 3, v30
	v_mad_i64_i32 v[34:35], s[18:19], v30, s65, 0
	v_mul_lo_u32 v42, v30, s40
	v_and_or_b32 v30, v30, s12, v39
	s_add_i32 s12, 0, 0x14000
	v_or3_b32 v30, v30, v40, v41
	s_add_u32 s18, s50, s38
	v_mov_b32_e32 v2, 0
	v_mul_u32_u24_e32 v36, 0xa0, v38
	v_add3_u32 v206, 0, v0, v42
	v_mul_lo_u32 v31, v31, s40
	v_or_b32_e32 v34, v34, v0
	v_or_b32_e32 v32, v32, v0
	v_mul_lo_u32 v30, v30, s40
	s_addc_u32 s19, s51, s39
	s_mov_b32 s8, 0
	s_mov_b64 s[36:37], 0
	v_mov_b32_e32 v3, v2
	v_mov_b32_e32 v4, v2
	v_mov_b32_e32 v5, v2
	v_mov_b32_e32 v50, v2
	v_mov_b32_e32 v51, v2
	v_add3_u32 v205, 0, v31, v37
	v_add3_u32 v119, s12, v36, v37
	v_lshl_add_u64 v[188:189], s[6:7], 0, v[32:33]
	v_add3_u32 v0, s12, v0, v30
	v_lshl_add_u64 v[190:191], s[18:19], 0, v[34:35]
	s_add_u32 s80, s18, 0x9504000
	s_addc_u32 s81, s19, 0
	s_add_u32 s86, s80, 0x1f0000
	s_addc_u32 s87, s81, 0
	s_add_u32 s96, s6, 0x1404000
	s_addc_u32 s97, s7, 0
	s_add_u32 s98, s96, 0x10000
	s_addc_u32 s99, s97, 0
	v_subrev_u32_e32 v190, s18, v190
	v_add_u32_e32 v191, 0xf8000, v190
	v_subrev_u32_e32 v188, s6, v188
	v_add_u32_e32 v207, 0xa000, v206
	global_load_dwordx4 v[228:231], v190, s[80:81] offset:128
	global_load_dwordx4 v[232:235], v191, s[80:81] offset:128
	global_load_dwordx4 v[236:239], v190, s[86:87] offset:128
	global_load_dwordx4 v[240:243], v191, s[86:87] offset:128
	global_load_dwordx4 v[244:247], v188, s[96:97] offset:128
	global_load_dwordx4 v[248:251], v188, s[98:99] offset:128
	global_load_dwordx4 v[66:69], v190, s[80:81] offset:256
	global_load_dwordx4 v[70:73], v191, s[80:81] offset:256
	global_load_dwordx4 v[74:77], v190, s[86:87] offset:256
	global_load_dwordx4 v[78:81], v191, s[86:87] offset:256
	global_load_dwordx4 v[82:85], v188, s[96:97] offset:256
	global_load_dwordx4 v[86:89], v188, s[98:99] offset:256
	s_barrier
	v_mov_b32_e32 v52, v2
	v_mov_b32_e32 v53, v2
	v_mov_b32_e32 v54, v2
	v_mov_b32_e32 v55, v2
	v_mov_b32_e32 v56, v2
	v_mov_b32_e32 v57, v2
	v_mov_b32_e32 v58, v2
	v_mov_b32_e32 v59, v2
	v_mov_b32_e32 v60, v2
	v_mov_b32_e32 v61, v2
	v_mov_b32_e32 v62, v2
	s_waitcnt vmcnt(17)
	ds_write_b128 v206, v[6:9]
	s_waitcnt vmcnt(16)
	ds_write_b128 v206, v[10:13] offset:10240
	s_waitcnt vmcnt(15)
	ds_write_b128 v206, v[14:17] offset:20480
	s_waitcnt vmcnt(14)
	ds_write_b128 v206, v[18:21] offset:30720
	s_waitcnt vmcnt(13)
	ds_write_b128 v0, v[22:25]
	s_waitcnt vmcnt(12)
	ds_write_b128 v0, v[26:29] offset:10240
	v_mov_b32_e32 v63, v2
	v_mov_b32_e32 v64, v2
	v_mov_b32_e32 v65, v2
	v_mov_b32_e32 v18, v2
	v_mov_b32_e32 v19, v2
	v_mov_b32_e32 v20, v2
	v_mov_b32_e32 v21, v2
	v_mov_b32_e32 v22, v2
	v_mov_b32_e32 v23, v2
	v_mov_b32_e32 v24, v2
	v_mov_b32_e32 v25, v2
	v_mov_b32_e32 v34, v2
	v_mov_b32_e32 v35, v2
	v_mov_b32_e32 v36, v2
	v_mov_b32_e32 v37, v2
	v_mov_b32_e32 v10, v2
	v_mov_b32_e32 v11, v2
	v_mov_b32_e32 v12, v2
	v_mov_b32_e32 v13, v2
	v_mov_b32_e32 v14, v2
	v_mov_b32_e32 v15, v2
	v_mov_b32_e32 v16, v2
	v_mov_b32_e32 v17, v2
	v_mov_b32_e32 v26, v2
	v_mov_b32_e32 v27, v2
	v_mov_b32_e32 v28, v2
	v_mov_b32_e32 v29, v2
	v_mov_b32_e32 v46, v2
	v_mov_b32_e32 v47, v2
	v_mov_b32_e32 v48, v2
	v_mov_b32_e32 v49, v2
	v_mov_b32_e32 v42, v2
	v_mov_b32_e32 v43, v2
	v_mov_b32_e32 v44, v2
	v_mov_b32_e32 v45, v2
	v_mov_b32_e32 v38, v2
	v_mov_b32_e32 v39, v2
	v_mov_b32_e32 v40, v2
	v_mov_b32_e32 v41, v2
	v_mov_b32_e32 v30, v2
	v_mov_b32_e32 v31, v2
	v_mov_b32_e32 v32, v2
	v_mov_b32_e32 v33, v2
	v_mov_b32_e32 v6, v2
	v_mov_b32_e32 v7, v2
	v_mov_b32_e32 v8, v2
	v_mov_b32_e32 v9, v2
	s_waitcnt lgkmcnt(0)
	s_barrier
.LBB0_1010:
	ds_read_b128 v[90:93], v119 offset:0
	ds_read_b128 v[208:211], v205 offset:0
	ds_read_b128 v[212:215], v119 offset:2560
	ds_read_b128 v[216:219], v119 offset:5120
	ds_read_b128 v[220:223], v119 offset:7680
	s_waitcnt lgkmcnt(3)
	v_mfma_f32_16x16x32_bf16 v[6:9], v[90:93], v[208:211], v[6:9]
	s_waitcnt lgkmcnt(2)
	v_mfma_f32_16x16x32_bf16 v[30:33], v[212:215], v[208:211], v[30:33]
	s_waitcnt vmcnt(11)
	ds_write_b128 v207, v[228:231] offset:0
	s_waitcnt lgkmcnt(2)
	v_mfma_f32_16x16x32_bf16 v[38:41], v[216:219], v[208:211], v[38:41]
	s_waitcnt lgkmcnt(1)
	v_mfma_f32_16x16x32_bf16 v[42:45], v[220:223], v[208:211], v[42:45]
	ds_read_b128 v[208:211], v205 offset:2560
	s_waitcnt lgkmcnt(0)
	v_mfma_f32_16x16x32_bf16 v[46:49], v[90:93], v[208:211], v[46:49]
	v_mfma_f32_16x16x32_bf16 v[26:29], v[212:215], v[208:211], v[26:29]
	s_waitcnt vmcnt(10)
	ds_write_b128 v207, v[232:235] offset:10240
	v_mfma_f32_16x16x32_bf16 v[14:17], v[216:219], v[208:211], v[14:17]
	v_mfma_f32_16x16x32_bf16 v[10:13], v[220:223], v[208:211], v[10:13]
	ds_read_b128 v[208:211], v205 offset:5120
	s_waitcnt lgkmcnt(0)
	v_mfma_f32_16x16x32_bf16 v[34:37], v[90:93], v[208:211], v[34:37]
	v_mfma_f32_16x16x32_bf16 v[22:25], v[212:215], v[208:211], v[22:25]
	s_waitcnt vmcnt(9)
	ds_write_b128 v207, v[236:239] offset:20480
	v_mfma_f32_16x16x32_bf16 v[18:21], v[216:219], v[208:211], v[18:21]
	v_mfma_f32_16x16x32_bf16 v[62:65], v[220:223], v[208:211], v[62:65]
	ds_read_b128 v[208:211], v205 offset:7680
	s_waitcnt lgkmcnt(0)
	v_mfma_f32_16x16x32_bf16 v[58:61], v[90:93], v[208:211], v[58:61]
	ds_read_b128 v[90:93], v119 offset:64
	v_mfma_f32_16x16x32_bf16 v[54:57], v[212:215], v[208:211], v[54:57]
	s_waitcnt vmcnt(8)
	ds_write_b128 v207, v[240:243] offset:30720
	ds_read_b128 v[212:215], v119 offset:2624
	v_mfma_f32_16x16x32_bf16 v[50:53], v[216:219], v[208:211], v[50:53]
	ds_read_b128 v[216:219], v119 offset:5184
	v_mfma_f32_16x16x32_bf16 v[2:5], v[220:223], v[208:211], v[2:5]
	ds_read_b128 v[220:223], v119 offset:7744
	ds_read_b128 v[208:211], v205 offset:64
	ds_read_b128 v[224:227], v205 offset:7744
	s_waitcnt lgkmcnt(1)
	v_mfma_f32_16x16x32_bf16 v[6:9], v[90:93], v[208:211], v[6:9]
	v_mfma_f32_16x16x32_bf16 v[30:33], v[212:215], v[208:211], v[30:33]
	s_waitcnt vmcnt(7)
	ds_write_b128 v0, v[244:247] offset:20480
	v_mfma_f32_16x16x32_bf16 v[38:41], v[216:219], v[208:211], v[38:41]
	v_mfma_f32_16x16x32_bf16 v[42:45], v[220:223], v[208:211], v[42:45]
	ds_read_b128 v[208:211], v205 offset:2624
	s_waitcnt lgkmcnt(0)
	v_mfma_f32_16x16x32_bf16 v[46:49], v[90:93], v[208:211], v[46:49]
	v_mfma_f32_16x16x32_bf16 v[26:29], v[212:215], v[208:211], v[26:29]
	s_waitcnt vmcnt(6)
	ds_write_b128 v0, v[248:251] offset:30720
	v_mfma_f32_16x16x32_bf16 v[14:17], v[216:219], v[208:211], v[14:17]
	v_mfma_f32_16x16x32_bf16 v[10:13], v[220:223], v[208:211], v[10:13]
	ds_read_b128 v[208:211], v205 offset:5184
	s_waitcnt lgkmcnt(0)
	v_mfma_f32_16x16x32_bf16 v[34:37], v[90:93], v[208:211], v[34:37]
	v_mfma_f32_16x16x32_bf16 v[22:25], v[212:215], v[208:211], v[22:25]
	v_mfma_f32_16x16x32_bf16 v[18:21], v[216:219], v[208:211], v[18:21]
	v_mfma_f32_16x16x32_bf16 v[62:65], v[220:223], v[208:211], v[62:65]
	v_mfma_f32_16x16x32_bf16 v[58:61], v[90:93], v[224:227], v[58:61]
	s_waitcnt lgkmcnt(0)
	v_mfma_f32_16x16x32_bf16 v[54:57], v[212:215], v[224:227], v[54:57]
	s_barrier
	v_mfma_f32_16x16x32_bf16 v[50:53], v[216:219], v[224:227], v[50:53]
	v_mfma_f32_16x16x32_bf16 v[2:5], v[220:223], v[224:227], v[2:5]
	global_load_dwordx4 v[228:231], v190, s[80:81] offset:384
	global_load_dwordx4 v[232:235], v191, s[80:81] offset:384
	global_load_dwordx4 v[236:239], v190, s[86:87] offset:384
	global_load_dwordx4 v[240:243], v191, s[86:87] offset:384
	global_load_dwordx4 v[244:247], v188, s[96:97] offset:384
	global_load_dwordx4 v[248:251], v188, s[98:99] offset:384
	ds_read_b128 v[90:93], v119 offset:20480
	ds_read_b128 v[208:211], v205 offset:40960
	ds_read_b128 v[212:215], v119 offset:23040
	ds_read_b128 v[216:219], v119 offset:25600
	ds_read_b128 v[220:223], v119 offset:28160
	s_waitcnt lgkmcnt(3)
	v_mfma_f32_16x16x32_bf16 v[6:9], v[90:93], v[208:211], v[6:9]
	s_waitcnt lgkmcnt(2)
	v_mfma_f32_16x16x32_bf16 v[30:33], v[212:215], v[208:211], v[30:33]
	s_waitcnt vmcnt(11)
	ds_write_b128 v206, v[66:69] offset:0
	s_waitcnt lgkmcnt(2)
	v_mfma_f32_16x16x32_bf16 v[38:41], v[216:219], v[208:211], v[38:41]
	s_waitcnt lgkmcnt(1)
	v_mfma_f32_16x16x32_bf16 v[42:45], v[220:223], v[208:211], v[42:45]
	ds_read_b128 v[208:211], v205 offset:43520
	s_waitcnt lgkmcnt(0)
	v_mfma_f32_16x16x32_bf16 v[46:49], v[90:93], v[208:211], v[46:49]
	v_mfma_f32_16x16x32_bf16 v[26:29], v[212:215], v[208:211], v[26:29]
	s_waitcnt vmcnt(10)
	ds_write_b128 v206, v[70:73] offset:10240
	v_mfma_f32_16x16x32_bf16 v[14:17], v[216:219], v[208:211], v[14:17]
	v_mfma_f32_16x16x32_bf16 v[10:13], v[220:223], v[208:211], v[10:13]
	ds_read_b128 v[208:211], v205 offset:46080
	s_waitcnt lgkmcnt(0)
	v_mfma_f32_16x16x32_bf16 v[34:37], v[90:93], v[208:211], v[34:37]
	v_mfma_f32_16x16x32_bf16 v[22:25], v[212:215], v[208:211], v[22:25]
	s_waitcnt vmcnt(9)
	ds_write_b128 v206, v[74:77] offset:20480
	v_mfma_f32_16x16x32_bf16 v[18:21], v[216:219], v[208:211], v[18:21]
	v_mfma_f32_16x16x32_bf16 v[62:65], v[220:223], v[208:211], v[62:65]
	ds_read_b128 v[208:211], v205 offset:48640
	s_waitcnt lgkmcnt(0)
	v_mfma_f32_16x16x32_bf16 v[58:61], v[90:93], v[208:211], v[58:61]
	ds_read_b128 v[90:93], v119 offset:20544
	v_mfma_f32_16x16x32_bf16 v[54:57], v[212:215], v[208:211], v[54:57]
	s_waitcnt vmcnt(8)
	ds_write_b128 v206, v[78:81] offset:30720
	ds_read_b128 v[212:215], v119 offset:23104
	v_mfma_f32_16x16x32_bf16 v[50:53], v[216:219], v[208:211], v[50:53]
	ds_read_b128 v[216:219], v119 offset:25664
	v_mfma_f32_16x16x32_bf16 v[2:5], v[220:223], v[208:211], v[2:5]
	ds_read_b128 v[220:223], v119 offset:28224
	ds_read_b128 v[208:211], v205 offset:41024
	ds_read_b128 v[224:227], v205 offset:48704
	s_waitcnt lgkmcnt(1)
	v_mfma_f32_16x16x32_bf16 v[6:9], v[90:93], v[208:211], v[6:9]
	v_mfma_f32_16x16x32_bf16 v[30:33], v[212:215], v[208:211], v[30:33]
	s_waitcnt vmcnt(7)
	ds_write_b128 v0, v[82:85] offset:0
	v_mfma_f32_16x16x32_bf16 v[38:41], v[216:219], v[208:211], v[38:41]
	v_mfma_f32_16x16x32_bf16 v[42:45], v[220:223], v[208:211], v[42:45]
	ds_read_b128 v[208:211], v205 offset:43584
	s_waitcnt lgkmcnt(0)
	v_mfma_f32_16x16x32_bf16 v[46:49], v[90:93], v[208:211], v[46:49]
	v_mfma_f32_16x16x32_bf16 v[26:29], v[212:215], v[208:211], v[26:29]
	s_waitcnt vmcnt(6)
	ds_write_b128 v0, v[86:89] offset:10240
	v_mfma_f32_16x16x32_bf16 v[14:17], v[216:219], v[208:211], v[14:17]
	v_mfma_f32_16x16x32_bf16 v[10:13], v[220:223], v[208:211], v[10:13]
	ds_read_b128 v[208:211], v205 offset:46144
	s_waitcnt lgkmcnt(0)
	v_mfma_f32_16x16x32_bf16 v[34:37], v[90:93], v[208:211], v[34:37]
	v_mfma_f32_16x16x32_bf16 v[22:25], v[212:215], v[208:211], v[22:25]
	v_mfma_f32_16x16x32_bf16 v[18:21], v[216:219], v[208:211], v[18:21]
	v_mfma_f32_16x16x32_bf16 v[62:65], v[220:223], v[208:211], v[62:65]
	v_mfma_f32_16x16x32_bf16 v[58:61], v[90:93], v[224:227], v[58:61]
	s_waitcnt lgkmcnt(0)
	v_mfma_f32_16x16x32_bf16 v[54:57], v[212:215], v[224:227], v[54:57]
	s_barrier
	v_mfma_f32_16x16x32_bf16 v[50:53], v[216:219], v[224:227], v[50:53]
	v_mfma_f32_16x16x32_bf16 v[2:5], v[220:223], v[224:227], v[2:5]
	global_load_dwordx4 v[66:69], v190, s[80:81] offset:512
	global_load_dwordx4 v[70:73], v191, s[80:81] offset:512
	global_load_dwordx4 v[74:77], v190, s[86:87] offset:512
	global_load_dwordx4 v[78:81], v191, s[86:87] offset:512
	global_load_dwordx4 v[82:85], v188, s[96:97] offset:512
	global_load_dwordx4 v[86:89], v188, s[98:99] offset:512
	ds_read_b128 v[90:93], v119 offset:0
	ds_read_b128 v[208:211], v205 offset:0
	ds_read_b128 v[212:215], v119 offset:2560
	ds_read_b128 v[216:219], v119 offset:5120
	ds_read_b128 v[220:223], v119 offset:7680
	s_waitcnt lgkmcnt(3)
	v_mfma_f32_16x16x32_bf16 v[6:9], v[90:93], v[208:211], v[6:9]
	s_waitcnt lgkmcnt(2)
	v_mfma_f32_16x16x32_bf16 v[30:33], v[212:215], v[208:211], v[30:33]
	s_waitcnt vmcnt(11)
	ds_write_b128 v207, v[228:231] offset:0
	s_waitcnt lgkmcnt(2)
	v_mfma_f32_16x16x32_bf16 v[38:41], v[216:219], v[208:211], v[38:41]
	s_waitcnt lgkmcnt(1)
	v_mfma_f32_16x16x32_bf16 v[42:45], v[220:223], v[208:211], v[42:45]
	ds_read_b128 v[208:211], v205 offset:2560
	s_waitcnt lgkmcnt(0)
	v_mfma_f32_16x16x32_bf16 v[46:49], v[90:93], v[208:211], v[46:49]
	v_mfma_f32_16x16x32_bf16 v[26:29], v[212:215], v[208:211], v[26:29]
	s_waitcnt vmcnt(10)
	ds_write_b128 v207, v[232:235] offset:10240
	v_mfma_f32_16x16x32_bf16 v[14:17], v[216:219], v[208:211], v[14:17]
	v_mfma_f32_16x16x32_bf16 v[10:13], v[220:223], v[208:211], v[10:13]
	ds_read_b128 v[208:211], v205 offset:5120
	s_waitcnt lgkmcnt(0)
	v_mfma_f32_16x16x32_bf16 v[34:37], v[90:93], v[208:211], v[34:37]
	v_mfma_f32_16x16x32_bf16 v[22:25], v[212:215], v[208:211], v[22:25]
	s_waitcnt vmcnt(9)
	ds_write_b128 v207, v[236:239] offset:20480
	v_mfma_f32_16x16x32_bf16 v[18:21], v[216:219], v[208:211], v[18:21]
	v_mfma_f32_16x16x32_bf16 v[62:65], v[220:223], v[208:211], v[62:65]
	ds_read_b128 v[208:211], v205 offset:7680
	s_waitcnt lgkmcnt(0)
	v_mfma_f32_16x16x32_bf16 v[58:61], v[90:93], v[208:211], v[58:61]
	ds_read_b128 v[90:93], v119 offset:64
	v_mfma_f32_16x16x32_bf16 v[54:57], v[212:215], v[208:211], v[54:57]
	s_waitcnt vmcnt(8)
	ds_write_b128 v207, v[240:243] offset:30720
	ds_read_b128 v[212:215], v119 offset:2624
	v_mfma_f32_16x16x32_bf16 v[50:53], v[216:219], v[208:211], v[50:53]
	ds_read_b128 v[216:219], v119 offset:5184
	v_mfma_f32_16x16x32_bf16 v[2:5], v[220:223], v[208:211], v[2:5]
	ds_read_b128 v[220:223], v119 offset:7744
	ds_read_b128 v[208:211], v205 offset:64
	ds_read_b128 v[224:227], v205 offset:7744
	s_waitcnt lgkmcnt(1)
	v_mfma_f32_16x16x32_bf16 v[6:9], v[90:93], v[208:211], v[6:9]
	v_mfma_f32_16x16x32_bf16 v[30:33], v[212:215], v[208:211], v[30:33]
	s_waitcnt vmcnt(7)
	ds_write_b128 v0, v[244:247] offset:20480
	v_mfma_f32_16x16x32_bf16 v[38:41], v[216:219], v[208:211], v[38:41]
	v_mfma_f32_16x16x32_bf16 v[42:45], v[220:223], v[208:211], v[42:45]
	ds_read_b128 v[208:211], v205 offset:2624
	s_waitcnt lgkmcnt(0)
	v_mfma_f32_16x16x32_bf16 v[46:49], v[90:93], v[208:211], v[46:49]
	v_mfma_f32_16x16x32_bf16 v[26:29], v[212:215], v[208:211], v[26:29]
	s_waitcnt vmcnt(6)
	ds_write_b128 v0, v[248:251] offset:30720
	v_mfma_f32_16x16x32_bf16 v[14:17], v[216:219], v[208:211], v[14:17]
	v_mfma_f32_16x16x32_bf16 v[10:13], v[220:223], v[208:211], v[10:13]
	ds_read_b128 v[208:211], v205 offset:5184
	s_waitcnt lgkmcnt(0)
	v_mfma_f32_16x16x32_bf16 v[34:37], v[90:93], v[208:211], v[34:37]
	v_mfma_f32_16x16x32_bf16 v[22:25], v[212:215], v[208:211], v[22:25]
	v_mfma_f32_16x16x32_bf16 v[18:21], v[216:219], v[208:211], v[18:21]
	v_mfma_f32_16x16x32_bf16 v[62:65], v[220:223], v[208:211], v[62:65]
	v_mfma_f32_16x16x32_bf16 v[58:61], v[90:93], v[224:227], v[58:61]
	s_waitcnt lgkmcnt(0)
	v_mfma_f32_16x16x32_bf16 v[54:57], v[212:215], v[224:227], v[54:57]
	s_barrier
	v_mfma_f32_16x16x32_bf16 v[50:53], v[216:219], v[224:227], v[50:53]
	v_mfma_f32_16x16x32_bf16 v[2:5], v[220:223], v[224:227], v[2:5]
	global_load_dwordx4 v[228:231], v190, s[80:81] offset:640
	global_load_dwordx4 v[232:235], v191, s[80:81] offset:640
	global_load_dwordx4 v[236:239], v190, s[86:87] offset:640
	global_load_dwordx4 v[240:243], v191, s[86:87] offset:640
	global_load_dwordx4 v[244:247], v188, s[96:97] offset:640
	global_load_dwordx4 v[248:251], v188, s[98:99] offset:640
	ds_read_b128 v[90:93], v119 offset:20480
	ds_read_b128 v[208:211], v205 offset:40960
	ds_read_b128 v[212:215], v119 offset:23040
	ds_read_b128 v[216:219], v119 offset:25600
	ds_read_b128 v[220:223], v119 offset:28160
	s_waitcnt lgkmcnt(3)
	v_mfma_f32_16x16x32_bf16 v[6:9], v[90:93], v[208:211], v[6:9]
	s_waitcnt lgkmcnt(2)
	v_mfma_f32_16x16x32_bf16 v[30:33], v[212:215], v[208:211], v[30:33]
	s_waitcnt vmcnt(11)
	ds_write_b128 v206, v[66:69] offset:0
	s_waitcnt lgkmcnt(2)
	v_mfma_f32_16x16x32_bf16 v[38:41], v[216:219], v[208:211], v[38:41]
	s_waitcnt lgkmcnt(1)
	v_mfma_f32_16x16x32_bf16 v[42:45], v[220:223], v[208:211], v[42:45]
	ds_read_b128 v[208:211], v205 offset:43520
	s_waitcnt lgkmcnt(0)
	v_mfma_f32_16x16x32_bf16 v[46:49], v[90:93], v[208:211], v[46:49]
	v_mfma_f32_16x16x32_bf16 v[26:29], v[212:215], v[208:211], v[26:29]
	s_waitcnt vmcnt(10)
	ds_write_b128 v206, v[70:73] offset:10240
	v_mfma_f32_16x16x32_bf16 v[14:17], v[216:219], v[208:211], v[14:17]
	v_mfma_f32_16x16x32_bf16 v[10:13], v[220:223], v[208:211], v[10:13]
	ds_read_b128 v[208:211], v205 offset:46080
	s_waitcnt lgkmcnt(0)
	v_mfma_f32_16x16x32_bf16 v[34:37], v[90:93], v[208:211], v[34:37]
	v_mfma_f32_16x16x32_bf16 v[22:25], v[212:215], v[208:211], v[22:25]
	s_waitcnt vmcnt(9)
	ds_write_b128 v206, v[74:77] offset:20480
	v_mfma_f32_16x16x32_bf16 v[18:21], v[216:219], v[208:211], v[18:21]
	v_mfma_f32_16x16x32_bf16 v[62:65], v[220:223], v[208:211], v[62:65]
	ds_read_b128 v[208:211], v205 offset:48640
	s_waitcnt lgkmcnt(0)
	v_mfma_f32_16x16x32_bf16 v[58:61], v[90:93], v[208:211], v[58:61]
	ds_read_b128 v[90:93], v119 offset:20544
	v_mfma_f32_16x16x32_bf16 v[54:57], v[212:215], v[208:211], v[54:57]
	s_waitcnt vmcnt(8)
	ds_write_b128 v206, v[78:81] offset:30720
	ds_read_b128 v[212:215], v119 offset:23104
	v_mfma_f32_16x16x32_bf16 v[50:53], v[216:219], v[208:211], v[50:53]
	ds_read_b128 v[216:219], v119 offset:25664
	v_mfma_f32_16x16x32_bf16 v[2:5], v[220:223], v[208:211], v[2:5]
	ds_read_b128 v[220:223], v119 offset:28224
	ds_read_b128 v[208:211], v205 offset:41024
	ds_read_b128 v[224:227], v205 offset:48704
	s_waitcnt lgkmcnt(1)
	v_mfma_f32_16x16x32_bf16 v[6:9], v[90:93], v[208:211], v[6:9]
	v_mfma_f32_16x16x32_bf16 v[30:33], v[212:215], v[208:211], v[30:33]
	s_waitcnt vmcnt(7)
	ds_write_b128 v0, v[82:85] offset:0
	v_mfma_f32_16x16x32_bf16 v[38:41], v[216:219], v[208:211], v[38:41]
	v_mfma_f32_16x16x32_bf16 v[42:45], v[220:223], v[208:211], v[42:45]
	ds_read_b128 v[208:211], v205 offset:43584
	s_waitcnt lgkmcnt(0)
	v_mfma_f32_16x16x32_bf16 v[46:49], v[90:93], v[208:211], v[46:49]
	v_mfma_f32_16x16x32_bf16 v[26:29], v[212:215], v[208:211], v[26:29]
	s_waitcnt vmcnt(6)
	ds_write_b128 v0, v[86:89] offset:10240
	v_mfma_f32_16x16x32_bf16 v[14:17], v[216:219], v[208:211], v[14:17]
	v_mfma_f32_16x16x32_bf16 v[10:13], v[220:223], v[208:211], v[10:13]
	ds_read_b128 v[208:211], v205 offset:46144
	s_waitcnt lgkmcnt(0)
	v_mfma_f32_16x16x32_bf16 v[34:37], v[90:93], v[208:211], v[34:37]
	v_mfma_f32_16x16x32_bf16 v[22:25], v[212:215], v[208:211], v[22:25]
	v_mfma_f32_16x16x32_bf16 v[18:21], v[216:219], v[208:211], v[18:21]
	v_mfma_f32_16x16x32_bf16 v[62:65], v[220:223], v[208:211], v[62:65]
	v_mfma_f32_16x16x32_bf16 v[58:61], v[90:93], v[224:227], v[58:61]
	s_waitcnt lgkmcnt(0)
	v_mfma_f32_16x16x32_bf16 v[54:57], v[212:215], v[224:227], v[54:57]
	s_barrier
	v_mfma_f32_16x16x32_bf16 v[50:53], v[216:219], v[224:227], v[50:53]
	v_mfma_f32_16x16x32_bf16 v[2:5], v[220:223], v[224:227], v[2:5]
	global_load_dwordx4 v[66:69], v190, s[80:81] offset:768
	global_load_dwordx4 v[70:73], v191, s[80:81] offset:768
	global_load_dwordx4 v[74:77], v190, s[86:87] offset:768
	global_load_dwordx4 v[78:81], v191, s[86:87] offset:768
	global_load_dwordx4 v[82:85], v188, s[96:97] offset:768
	global_load_dwordx4 v[86:89], v188, s[98:99] offset:768
	ds_read_b128 v[90:93], v119 offset:0
	ds_read_b128 v[208:211], v205 offset:0
	ds_read_b128 v[212:215], v119 offset:2560
	ds_read_b128 v[216:219], v119 offset:5120
	ds_read_b128 v[220:223], v119 offset:7680
	s_waitcnt lgkmcnt(3)
	v_mfma_f32_16x16x32_bf16 v[6:9], v[90:93], v[208:211], v[6:9]
	s_waitcnt lgkmcnt(2)
	v_mfma_f32_16x16x32_bf16 v[30:33], v[212:215], v[208:211], v[30:33]
	s_waitcnt vmcnt(11)
	ds_write_b128 v207, v[228:231] offset:0
	s_waitcnt lgkmcnt(2)
	v_mfma_f32_16x16x32_bf16 v[38:41], v[216:219], v[208:211], v[38:41]
	s_waitcnt lgkmcnt(1)
	v_mfma_f32_16x16x32_bf16 v[42:45], v[220:223], v[208:211], v[42:45]
	ds_read_b128 v[208:211], v205 offset:2560
	s_waitcnt lgkmcnt(0)
	v_mfma_f32_16x16x32_bf16 v[46:49], v[90:93], v[208:211], v[46:49]
	v_mfma_f32_16x16x32_bf16 v[26:29], v[212:215], v[208:211], v[26:29]
	s_waitcnt vmcnt(10)
	ds_write_b128 v207, v[232:235] offset:10240
	v_mfma_f32_16x16x32_bf16 v[14:17], v[216:219], v[208:211], v[14:17]
	v_mfma_f32_16x16x32_bf16 v[10:13], v[220:223], v[208:211], v[10:13]
	ds_read_b128 v[208:211], v205 offset:5120
	s_waitcnt lgkmcnt(0)
	v_mfma_f32_16x16x32_bf16 v[34:37], v[90:93], v[208:211], v[34:37]
	v_mfma_f32_16x16x32_bf16 v[22:25], v[212:215], v[208:211], v[22:25]
	s_waitcnt vmcnt(9)
	ds_write_b128 v207, v[236:239] offset:20480
	v_mfma_f32_16x16x32_bf16 v[18:21], v[216:219], v[208:211], v[18:21]
	v_mfma_f32_16x16x32_bf16 v[62:65], v[220:223], v[208:211], v[62:65]
	ds_read_b128 v[208:211], v205 offset:7680
	s_waitcnt lgkmcnt(0)
	v_mfma_f32_16x16x32_bf16 v[58:61], v[90:93], v[208:211], v[58:61]
	ds_read_b128 v[90:93], v119 offset:64
	v_mfma_f32_16x16x32_bf16 v[54:57], v[212:215], v[208:211], v[54:57]
	s_waitcnt vmcnt(8)
	ds_write_b128 v207, v[240:243] offset:30720
	ds_read_b128 v[212:215], v119 offset:2624
	v_mfma_f32_16x16x32_bf16 v[50:53], v[216:219], v[208:211], v[50:53]
	ds_read_b128 v[216:219], v119 offset:5184
	v_mfma_f32_16x16x32_bf16 v[2:5], v[220:223], v[208:211], v[2:5]
	ds_read_b128 v[220:223], v119 offset:7744
	ds_read_b128 v[208:211], v205 offset:64
	ds_read_b128 v[224:227], v205 offset:7744
	s_waitcnt lgkmcnt(1)
	v_mfma_f32_16x16x32_bf16 v[6:9], v[90:93], v[208:211], v[6:9]
	v_mfma_f32_16x16x32_bf16 v[30:33], v[212:215], v[208:211], v[30:33]
	s_waitcnt vmcnt(7)
	ds_write_b128 v0, v[244:247] offset:20480
	v_mfma_f32_16x16x32_bf16 v[38:41], v[216:219], v[208:211], v[38:41]
	v_mfma_f32_16x16x32_bf16 v[42:45], v[220:223], v[208:211], v[42:45]
	ds_read_b128 v[208:211], v205 offset:2624
	s_waitcnt lgkmcnt(0)
	v_mfma_f32_16x16x32_bf16 v[46:49], v[90:93], v[208:211], v[46:49]
	v_mfma_f32_16x16x32_bf16 v[26:29], v[212:215], v[208:211], v[26:29]
	s_waitcnt vmcnt(6)
	ds_write_b128 v0, v[248:251] offset:30720
	v_mfma_f32_16x16x32_bf16 v[14:17], v[216:219], v[208:211], v[14:17]
	v_mfma_f32_16x16x32_bf16 v[10:13], v[220:223], v[208:211], v[10:13]
	ds_read_b128 v[208:211], v205 offset:5184
	s_waitcnt lgkmcnt(0)
	v_mfma_f32_16x16x32_bf16 v[34:37], v[90:93], v[208:211], v[34:37]
	v_mfma_f32_16x16x32_bf16 v[22:25], v[212:215], v[208:211], v[22:25]
	v_mfma_f32_16x16x32_bf16 v[18:21], v[216:219], v[208:211], v[18:21]
	v_mfma_f32_16x16x32_bf16 v[62:65], v[220:223], v[208:211], v[62:65]
	v_mfma_f32_16x16x32_bf16 v[58:61], v[90:93], v[224:227], v[58:61]
	s_waitcnt lgkmcnt(0)
	v_mfma_f32_16x16x32_bf16 v[54:57], v[212:215], v[224:227], v[54:57]
	s_barrier
	v_mfma_f32_16x16x32_bf16 v[50:53], v[216:219], v[224:227], v[50:53]
	v_mfma_f32_16x16x32_bf16 v[2:5], v[220:223], v[224:227], v[2:5]
	global_load_dwordx4 v[228:231], v190, s[80:81] offset:896
	global_load_dwordx4 v[232:235], v191, s[80:81] offset:896
	global_load_dwordx4 v[236:239], v190, s[86:87] offset:896
	global_load_dwordx4 v[240:243], v191, s[86:87] offset:896
	global_load_dwordx4 v[244:247], v188, s[96:97] offset:896
	global_load_dwordx4 v[248:251], v188, s[98:99] offset:896
	ds_read_b128 v[90:93], v119 offset:20480
	ds_read_b128 v[208:211], v205 offset:40960
	ds_read_b128 v[212:215], v119 offset:23040
	ds_read_b128 v[216:219], v119 offset:25600
	ds_read_b128 v[220:223], v119 offset:28160
	s_waitcnt lgkmcnt(3)
	v_mfma_f32_16x16x32_bf16 v[6:9], v[90:93], v[208:211], v[6:9]
	s_waitcnt lgkmcnt(2)
	v_mfma_f32_16x16x32_bf16 v[30:33], v[212:215], v[208:211], v[30:33]
	s_waitcnt vmcnt(11)
	ds_write_b128 v206, v[66:69] offset:0
	s_waitcnt lgkmcnt(2)
	v_mfma_f32_16x16x32_bf16 v[38:41], v[216:219], v[208:211], v[38:41]
	s_waitcnt lgkmcnt(1)
	v_mfma_f32_16x16x32_bf16 v[42:45], v[220:223], v[208:211], v[42:45]
	ds_read_b128 v[208:211], v205 offset:43520
	s_waitcnt lgkmcnt(0)
	v_mfma_f32_16x16x32_bf16 v[46:49], v[90:93], v[208:211], v[46:49]
	v_mfma_f32_16x16x32_bf16 v[26:29], v[212:215], v[208:211], v[26:29]
	s_waitcnt vmcnt(10)
	ds_write_b128 v206, v[70:73] offset:10240
	v_mfma_f32_16x16x32_bf16 v[14:17], v[216:219], v[208:211], v[14:17]
	v_mfma_f32_16x16x32_bf16 v[10:13], v[220:223], v[208:211], v[10:13]
	ds_read_b128 v[208:211], v205 offset:46080
	s_waitcnt lgkmcnt(0)
	v_mfma_f32_16x16x32_bf16 v[34:37], v[90:93], v[208:211], v[34:37]
	v_mfma_f32_16x16x32_bf16 v[22:25], v[212:215], v[208:211], v[22:25]
	s_waitcnt vmcnt(9)
	ds_write_b128 v206, v[74:77] offset:20480
	v_mfma_f32_16x16x32_bf16 v[18:21], v[216:219], v[208:211], v[18:21]
	v_mfma_f32_16x16x32_bf16 v[62:65], v[220:223], v[208:211], v[62:65]
	ds_read_b128 v[208:211], v205 offset:48640
	s_waitcnt lgkmcnt(0)
	v_mfma_f32_16x16x32_bf16 v[58:61], v[90:93], v[208:211], v[58:61]
	ds_read_b128 v[90:93], v119 offset:20544
	v_mfma_f32_16x16x32_bf16 v[54:57], v[212:215], v[208:211], v[54:57]
	s_waitcnt vmcnt(8)
	ds_write_b128 v206, v[78:81] offset:30720
	ds_read_b128 v[212:215], v119 offset:23104
	v_mfma_f32_16x16x32_bf16 v[50:53], v[216:219], v[208:211], v[50:53]
	ds_read_b128 v[216:219], v119 offset:25664
	v_mfma_f32_16x16x32_bf16 v[2:5], v[220:223], v[208:211], v[2:5]
	ds_read_b128 v[220:223], v119 offset:28224
	ds_read_b128 v[208:211], v205 offset:41024
	ds_read_b128 v[224:227], v205 offset:48704
	s_waitcnt lgkmcnt(1)
	v_mfma_f32_16x16x32_bf16 v[6:9], v[90:93], v[208:211], v[6:9]
	v_mfma_f32_16x16x32_bf16 v[30:33], v[212:215], v[208:211], v[30:33]
	s_waitcnt vmcnt(7)
	ds_write_b128 v0, v[82:85] offset:0
	v_mfma_f32_16x16x32_bf16 v[38:41], v[216:219], v[208:211], v[38:41]
	v_mfma_f32_16x16x32_bf16 v[42:45], v[220:223], v[208:211], v[42:45]
	ds_read_b128 v[208:211], v205 offset:43584
	s_waitcnt lgkmcnt(0)
	v_mfma_f32_16x16x32_bf16 v[46:49], v[90:93], v[208:211], v[46:49]
	v_mfma_f32_16x16x32_bf16 v[26:29], v[212:215], v[208:211], v[26:29]
	s_waitcnt vmcnt(6)
	ds_write_b128 v0, v[86:89] offset:10240
	s_lshl_b32 s10, s66, 10
	s_mov_b32 s11, 0
	v_lshl_add_u64 v[82:83], v[128:129], 0, s[10:11]
	v_lshl_add_u64 v[84:85], v[132:133], 0, s[10:11]
	v_lshl_add_u64 v[86:87], v[152:153], 0, s[10:11]
	v_lshl_add_u64 v[88:89], v[154:155], 0, s[10:11]
	global_load_dwordx2 v[66:67], v[82:83], off
	global_load_dwordx2 v[68:69], v[82:83], off offset:32
	global_load_dwordx2 v[70:71], v[84:85], off
	global_load_dwordx2 v[72:73], v[84:85], off offset:32
	global_load_dwordx2 v[74:75], v[86:87], off
	global_load_dwordx2 v[76:77], v[86:87], off offset:32
	global_load_dwordx2 v[78:79], v[88:89], off
	global_load_dwordx2 v[80:81], v[88:89], off offset:32
	v_mfma_f32_16x16x32_bf16 v[14:17], v[216:219], v[208:211], v[14:17]
	v_mfma_f32_16x16x32_bf16 v[10:13], v[220:223], v[208:211], v[10:13]
	ds_read_b128 v[208:211], v205 offset:46144
	s_waitcnt lgkmcnt(0)
	v_mfma_f32_16x16x32_bf16 v[34:37], v[90:93], v[208:211], v[34:37]
	v_mfma_f32_16x16x32_bf16 v[22:25], v[212:215], v[208:211], v[22:25]
	v_mfma_f32_16x16x32_bf16 v[18:21], v[216:219], v[208:211], v[18:21]
	v_mfma_f32_16x16x32_bf16 v[62:65], v[220:223], v[208:211], v[62:65]
	v_mfma_f32_16x16x32_bf16 v[58:61], v[90:93], v[224:227], v[58:61]
	s_waitcnt lgkmcnt(0)
	v_mfma_f32_16x16x32_bf16 v[54:57], v[212:215], v[224:227], v[54:57]
	s_barrier
	v_mfma_f32_16x16x32_bf16 v[50:53], v[216:219], v[224:227], v[50:53]
	v_mfma_f32_16x16x32_bf16 v[2:5], v[220:223], v[224:227], v[2:5]
	ds_read_b128 v[90:93], v119 offset:0
	ds_read_b128 v[208:211], v205 offset:0
	ds_read_b128 v[212:215], v119 offset:2560
	ds_read_b128 v[216:219], v119 offset:5120
	ds_read_b128 v[220:223], v119 offset:7680
	s_waitcnt lgkmcnt(3)
	v_mfma_f32_16x16x32_bf16 v[6:9], v[90:93], v[208:211], v[6:9]
	s_waitcnt lgkmcnt(2)
	v_mfma_f32_16x16x32_bf16 v[30:33], v[212:215], v[208:211], v[30:33]
	s_waitcnt vmcnt(13)
	ds_write_b128 v207, v[228:231] offset:0
	s_waitcnt lgkmcnt(2)
	v_mfma_f32_16x16x32_bf16 v[38:41], v[216:219], v[208:211], v[38:41]
	s_waitcnt lgkmcnt(1)
	v_mfma_f32_16x16x32_bf16 v[42:45], v[220:223], v[208:211], v[42:45]
	ds_read_b128 v[208:211], v205 offset:2560
	s_waitcnt lgkmcnt(0)
	v_mfma_f32_16x16x32_bf16 v[46:49], v[90:93], v[208:211], v[46:49]
	v_mfma_f32_16x16x32_bf16 v[26:29], v[212:215], v[208:211], v[26:29]
	s_waitcnt vmcnt(12)
	ds_write_b128 v207, v[232:235] offset:10240
	v_mfma_f32_16x16x32_bf16 v[14:17], v[216:219], v[208:211], v[14:17]
	v_mfma_f32_16x16x32_bf16 v[10:13], v[220:223], v[208:211], v[10:13]
	ds_read_b128 v[208:211], v205 offset:5120
	s_waitcnt lgkmcnt(0)
	v_mfma_f32_16x16x32_bf16 v[34:37], v[90:93], v[208:211], v[34:37]
	v_mfma_f32_16x16x32_bf16 v[22:25], v[212:215], v[208:211], v[22:25]
	s_waitcnt vmcnt(11)
	ds_write_b128 v207, v[236:239] offset:20480
	v_mfma_f32_16x16x32_bf16 v[18:21], v[216:219], v[208:211], v[18:21]
	v_mfma_f32_16x16x32_bf16 v[62:65], v[220:223], v[208:211], v[62:65]
	ds_read_b128 v[208:211], v205 offset:7680
	s_waitcnt lgkmcnt(0)
	v_mfma_f32_16x16x32_bf16 v[58:61], v[90:93], v[208:211], v[58:61]
	ds_read_b128 v[90:93], v119 offset:64
	v_mfma_f32_16x16x32_bf16 v[54:57], v[212:215], v[208:211], v[54:57]
	s_waitcnt vmcnt(10)
	ds_write_b128 v207, v[240:243] offset:30720
	ds_read_b128 v[212:215], v119 offset:2624
	v_mfma_f32_16x16x32_bf16 v[50:53], v[216:219], v[208:211], v[50:53]
	ds_read_b128 v[216:219], v119 offset:5184
	v_mfma_f32_16x16x32_bf16 v[2:5], v[220:223], v[208:211], v[2:5]
	ds_read_b128 v[220:223], v119 offset:7744
	ds_read_b128 v[208:211], v205 offset:64
	ds_read_b128 v[224:227], v205 offset:7744
	s_waitcnt lgkmcnt(1)
	v_mfma_f32_16x16x32_bf16 v[6:9], v[90:93], v[208:211], v[6:9]
	v_mfma_f32_16x16x32_bf16 v[30:33], v[212:215], v[208:211], v[30:33]
	s_waitcnt vmcnt(9)
	ds_write_b128 v0, v[244:247] offset:20480
	v_mfma_f32_16x16x32_bf16 v[38:41], v[216:219], v[208:211], v[38:41]
	v_mfma_f32_16x16x32_bf16 v[42:45], v[220:223], v[208:211], v[42:45]
	ds_read_b128 v[208:211], v205 offset:2624
	s_waitcnt lgkmcnt(0)
	v_mfma_f32_16x16x32_bf16 v[46:49], v[90:93], v[208:211], v[46:49]
	v_mfma_f32_16x16x32_bf16 v[26:29], v[212:215], v[208:211], v[26:29]
	s_waitcnt vmcnt(8)
	ds_write_b128 v0, v[248:251] offset:30720
	v_mfma_f32_16x16x32_bf16 v[14:17], v[216:219], v[208:211], v[14:17]
	v_mfma_f32_16x16x32_bf16 v[10:13], v[220:223], v[208:211], v[10:13]
	ds_read_b128 v[208:211], v205 offset:5184
	s_waitcnt lgkmcnt(0)
	v_mfma_f32_16x16x32_bf16 v[34:37], v[90:93], v[208:211], v[34:37]
	v_mfma_f32_16x16x32_bf16 v[22:25], v[212:215], v[208:211], v[22:25]
	v_mfma_f32_16x16x32_bf16 v[18:21], v[216:219], v[208:211], v[18:21]
	v_mfma_f32_16x16x32_bf16 v[62:65], v[220:223], v[208:211], v[62:65]
	v_mfma_f32_16x16x32_bf16 v[58:61], v[90:93], v[224:227], v[58:61]
	s_waitcnt lgkmcnt(0)
	v_mfma_f32_16x16x32_bf16 v[54:57], v[212:215], v[224:227], v[54:57]
	s_barrier
	v_mfma_f32_16x16x32_bf16 v[50:53], v[216:219], v[224:227], v[50:53]
	v_mfma_f32_16x16x32_bf16 v[2:5], v[220:223], v[224:227], v[2:5]
	ds_read_b128 v[90:93], v119 offset:20480
	ds_read_b128 v[208:211], v205 offset:40960
	ds_read_b128 v[212:215], v119 offset:23040
	ds_read_b128 v[216:219], v119 offset:25600
	ds_read_b128 v[220:223], v119 offset:28160
	s_waitcnt lgkmcnt(3)
	v_mfma_f32_16x16x32_bf16 v[6:9], v[90:93], v[208:211], v[6:9]
	s_waitcnt lgkmcnt(2)
	v_mfma_f32_16x16x32_bf16 v[30:33], v[212:215], v[208:211], v[30:33]
	s_waitcnt lgkmcnt(1)
	v_mfma_f32_16x16x32_bf16 v[38:41], v[216:219], v[208:211], v[38:41]
	s_waitcnt lgkmcnt(0)
	v_mfma_f32_16x16x32_bf16 v[42:45], v[220:223], v[208:211], v[42:45]
	ds_read_b128 v[208:211], v205 offset:43520
	s_waitcnt lgkmcnt(0)
	v_mfma_f32_16x16x32_bf16 v[46:49], v[90:93], v[208:211], v[46:49]
	v_mfma_f32_16x16x32_bf16 v[26:29], v[212:215], v[208:211], v[26:29]
	v_mfma_f32_16x16x32_bf16 v[14:17], v[216:219], v[208:211], v[14:17]
	v_mfma_f32_16x16x32_bf16 v[10:13], v[220:223], v[208:211], v[10:13]
	ds_read_b128 v[208:211], v205 offset:46080
	s_waitcnt lgkmcnt(0)
	v_mfma_f32_16x16x32_bf16 v[34:37], v[90:93], v[208:211], v[34:37]
	v_mfma_f32_16x16x32_bf16 v[22:25], v[212:215], v[208:211], v[22:25]
	v_mfma_f32_16x16x32_bf16 v[18:21], v[216:219], v[208:211], v[18:21]
	v_mfma_f32_16x16x32_bf16 v[62:65], v[220:223], v[208:211], v[62:65]
	ds_read_b128 v[208:211], v205 offset:48640
	s_waitcnt lgkmcnt(0)
	v_mfma_f32_16x16x32_bf16 v[58:61], v[90:93], v[208:211], v[58:61]
	ds_read_b128 v[90:93], v119 offset:20544
	v_mfma_f32_16x16x32_bf16 v[54:57], v[212:215], v[208:211], v[54:57]
	ds_read_b128 v[212:215], v119 offset:23104
	v_mfma_f32_16x16x32_bf16 v[50:53], v[216:219], v[208:211], v[50:53]
	ds_read_b128 v[216:219], v119 offset:25664
	v_mfma_f32_16x16x32_bf16 v[2:5], v[220:223], v[208:211], v[2:5]
	ds_read_b128 v[220:223], v119 offset:28224
	ds_read_b128 v[208:211], v205 offset:41024
	ds_read_b128 v[224:227], v205 offset:48704
	s_waitcnt lgkmcnt(1)
	v_mfma_f32_16x16x32_bf16 v[6:9], v[90:93], v[208:211], v[6:9]
	s_waitcnt vmcnt(0)
	v_mfma_f32_16x16x32_bf16 v[30:33], v[212:215], v[208:211], v[30:33]
	v_mfma_f32_16x16x32_bf16 v[38:41], v[216:219], v[208:211], v[38:41]
	v_mfma_f32_16x16x32_bf16 v[42:45], v[220:223], v[208:211], v[42:45]
	v_cvt_f32_ubyte0_e32 v86, v66
	v_cvt_f32_ubyte1_e32 v87, v66
	v_cvt_f32_ubyte2_e32 v88, v66
	v_cvt_f32_ubyte3_e32 v89, v66
	v_mul_f32_e32 v86, s34, v86
	v_mul_f32_e32 v87, s34, v87
	v_mul_f32_e32 v88, s34, v88
	v_mul_f32_e32 v89, s34, v89
	v_fma_f32 v184, v6, v86, v184
	v_fma_f32 v185, v7, v87, v185
	v_fma_f32 v186, v8, v88, v186
	v_fma_f32 v187, v9, v89, v187
	ds_read_b128 v[208:211], v205 offset:43584
	s_waitcnt lgkmcnt(0)
	v_mfma_f32_16x16x32_bf16 v[46:49], v[90:93], v[208:211], v[46:49]
	v_cvt_f32_ubyte0_e32 v82, v67
	v_cvt_f32_ubyte1_e32 v83, v67
	v_cvt_f32_ubyte2_e32 v84, v67
	v_cvt_f32_ubyte3_e32 v85, v67
	v_mul_f32_e32 v82, s34, v82
	v_mul_f32_e32 v83, s34, v83
	v_mul_f32_e32 v84, s34, v84
	v_mul_f32_e32 v85, s34, v85
	v_fma_f32 v180, v30, v82, v180
	v_fma_f32 v181, v31, v83, v181
	v_fma_f32 v182, v32, v84, v182
	v_fma_f32 v183, v33, v85, v183
	v_mfma_f32_16x16x32_bf16 v[26:29], v[212:215], v[208:211], v[26:29]
	v_cvt_f32_ubyte0_e32 v86, v68
	v_cvt_f32_ubyte1_e32 v87, v68
	v_cvt_f32_ubyte2_e32 v88, v68
	v_cvt_f32_ubyte3_e32 v89, v68
	v_mul_f32_e32 v86, s34, v86
	v_mul_f32_e32 v87, s34, v87
	v_mul_f32_e32 v88, s34, v88
	v_mul_f32_e32 v89, s34, v89
	v_fma_f32 v176, v38, v86, v176
	v_fma_f32 v177, v39, v87, v177
	v_fma_f32 v178, v40, v88, v178
	v_fma_f32 v179, v41, v89, v179
	v_mfma_f32_16x16x32_bf16 v[14:17], v[216:219], v[208:211], v[14:17]
	v_cvt_f32_ubyte0_e32 v82, v69
	v_cvt_f32_ubyte1_e32 v83, v69
	v_cvt_f32_ubyte2_e32 v84, v69
	v_cvt_f32_ubyte3_e32 v85, v69
	v_mul_f32_e32 v82, s34, v82
	v_mul_f32_e32 v83, s34, v83
	v_mul_f32_e32 v84, s34, v84
	v_mul_f32_e32 v85, s34, v85
	v_fma_f32 v172, v42, v82, v172
	v_fma_f32 v173, v43, v83, v173
	v_fma_f32 v174, v44, v84, v174
	v_fma_f32 v175, v45, v85, v175
	v_mfma_f32_16x16x32_bf16 v[10:13], v[220:223], v[208:211], v[10:13]
	v_cvt_f32_ubyte0_e32 v86, v70
	v_cvt_f32_ubyte1_e32 v87, v70
	v_cvt_f32_ubyte2_e32 v88, v70
	v_cvt_f32_ubyte3_e32 v89, v70
	v_mul_f32_e32 v86, s34, v86
	v_mul_f32_e32 v87, s34, v87
	v_mul_f32_e32 v88, s34, v88
	v_mul_f32_e32 v89, s34, v89
	v_fma_f32 v168, v46, v86, v168
	v_fma_f32 v169, v47, v87, v169
	v_fma_f32 v170, v48, v88, v170
	v_fma_f32 v171, v49, v89, v171
	ds_read_b128 v[208:211], v205 offset:46144
	s_waitcnt lgkmcnt(0)
	v_mfma_f32_16x16x32_bf16 v[34:37], v[90:93], v[208:211], v[34:37]
	v_cvt_f32_ubyte0_e32 v82, v71
	v_cvt_f32_ubyte1_e32 v83, v71
	v_cvt_f32_ubyte2_e32 v84, v71
	v_cvt_f32_ubyte3_e32 v85, v71
	v_mul_f32_e32 v82, s34, v82
	v_mul_f32_e32 v83, s34, v83
	v_mul_f32_e32 v84, s34, v84
	v_mul_f32_e32 v85, s34, v85
	v_fma_f32 v164, v26, v82, v164
	v_fma_f32 v165, v27, v83, v165
	v_fma_f32 v166, v28, v84, v166
	v_fma_f32 v167, v29, v85, v167
	v_mfma_f32_16x16x32_bf16 v[22:25], v[212:215], v[208:211], v[22:25]
	v_cvt_f32_ubyte0_e32 v86, v72
	v_cvt_f32_ubyte1_e32 v87, v72
	v_cvt_f32_ubyte2_e32 v88, v72
	v_cvt_f32_ubyte3_e32 v89, v72
	v_mul_f32_e32 v86, s34, v86
	v_mul_f32_e32 v87, s34, v87
	v_mul_f32_e32 v88, s34, v88
	v_mul_f32_e32 v89, s34, v89
	v_fma_f32 v160, v14, v86, v160
	v_fma_f32 v161, v15, v87, v161
	v_fma_f32 v162, v16, v88, v162
	v_fma_f32 v163, v17, v89, v163
	v_mfma_f32_16x16x32_bf16 v[18:21], v[216:219], v[208:211], v[18:21]
	v_cvt_f32_ubyte0_e32 v82, v73
	v_cvt_f32_ubyte1_e32 v83, v73
	v_cvt_f32_ubyte2_e32 v84, v73
	v_cvt_f32_ubyte3_e32 v85, v73
	v_mul_f32_e32 v82, s34, v82
	v_mul_f32_e32 v83, s34, v83
	v_mul_f32_e32 v84, s34, v84
	v_mul_f32_e32 v85, s34, v85
	v_fma_f32 v156, v10, v82, v156
	v_fma_f32 v157, v11, v83, v157
	v_fma_f32 v158, v12, v84, v158
	v_fma_f32 v159, v13, v85, v159
	v_mfma_f32_16x16x32_bf16 v[62:65], v[220:223], v[208:211], v[62:65]
	v_cvt_f32_ubyte0_e32 v86, v74
	v_cvt_f32_ubyte1_e32 v87, v74
	v_cvt_f32_ubyte2_e32 v88, v74
	v_cvt_f32_ubyte3_e32 v89, v74
	v_mul_f32_e32 v86, s34, v86
	v_mul_f32_e32 v87, s34, v87
	v_mul_f32_e32 v88, s34, v88
	v_mul_f32_e32 v89, s34, v89
	v_fma_f32 v136, v34, v86, v136
	v_fma_f32 v137, v35, v87, v137
	v_fma_f32 v150, v36, v88, v150
	v_fma_f32 v151, v37, v89, v151
	v_mfma_f32_16x16x32_bf16 v[58:61], v[90:93], v[224:227], v[58:61]
	v_cvt_f32_ubyte0_e32 v82, v75
	v_cvt_f32_ubyte1_e32 v83, v75
	v_cvt_f32_ubyte2_e32 v84, v75
	v_cvt_f32_ubyte3_e32 v85, v75
	v_mul_f32_e32 v82, s34, v82
	v_mul_f32_e32 v83, s34, v83
	v_mul_f32_e32 v84, s34, v84
	v_mul_f32_e32 v85, s34, v85
	v_fma_f32 v130, v22, v82, v130
	v_fma_f32 v131, v23, v83, v131
	v_fma_f32 v134, v24, v84, v134
	v_fma_f32 v135, v25, v85, v135
	v_mfma_f32_16x16x32_bf16 v[54:57], v[212:215], v[224:227], v[54:57]
	v_cvt_f32_ubyte0_e32 v86, v76
	v_cvt_f32_ubyte1_e32 v87, v76
	v_cvt_f32_ubyte2_e32 v88, v76
	v_cvt_f32_ubyte3_e32 v89, v76
	v_mul_f32_e32 v86, s34, v86
	v_mul_f32_e32 v87, s34, v87
	v_mul_f32_e32 v88, s34, v88
	v_mul_f32_e32 v89, s34, v89
	v_fma_f32 v124, v18, v86, v124
	v_fma_f32 v125, v19, v87, v125
	v_fma_f32 v126, v20, v88, v126
	v_fma_f32 v127, v21, v89, v127
	v_mfma_f32_16x16x32_bf16 v[50:53], v[216:219], v[224:227], v[50:53]
	v_cvt_f32_ubyte0_e32 v82, v77
	v_cvt_f32_ubyte1_e32 v83, v77
	v_cvt_f32_ubyte2_e32 v84, v77
	v_cvt_f32_ubyte3_e32 v85, v77
	v_mul_f32_e32 v82, s34, v82
	v_mul_f32_e32 v83, s34, v83
	v_mul_f32_e32 v84, s34, v84
	v_mul_f32_e32 v85, s34, v85
	v_fma_f32 v120, v62, v82, v120
	v_fma_f32 v121, v63, v83, v121
	v_fma_f32 v122, v64, v84, v122
	v_fma_f32 v123, v65, v85, v123
	v_mfma_f32_16x16x32_bf16 v[2:5], v[220:223], v[224:227], v[2:5]
	v_cvt_f32_ubyte0_e32 v86, v78
	v_cvt_f32_ubyte1_e32 v87, v78
	v_cvt_f32_ubyte2_e32 v88, v78
	v_cvt_f32_ubyte3_e32 v89, v78
	v_mul_f32_e32 v86, s34, v86
	v_mul_f32_e32 v87, s34, v87
	v_mul_f32_e32 v88, s34, v88
	v_mul_f32_e32 v89, s34, v89
	v_fma_f32 v114, v58, v86, v114
	v_fma_f32 v115, v59, v87, v115
	v_fma_f32 v116, v60, v88, v116
	v_fma_f32 v117, v61, v89, v117
	s_nop 7
	s_nop 3
	v_cvt_f32_ubyte0_e32 v86, v79
	v_cvt_f32_ubyte1_e32 v87, v79
	v_cvt_f32_ubyte2_e32 v88, v79
	v_cvt_f32_ubyte3_e32 v89, v79
	v_mul_f32_e32 v86, s34, v86
	v_mul_f32_e32 v87, s34, v87
	v_mul_f32_e32 v88, s34, v88
	v_mul_f32_e32 v89, s34, v89
	v_fma_f32 v106, v54, v86, v106
	v_fma_f32 v107, v55, v87, v107
	v_fma_f32 v108, v56, v88, v108
	v_fma_f32 v109, v57, v89, v109
	v_cvt_f32_ubyte0_e32 v82, v80
	v_cvt_f32_ubyte1_e32 v83, v80
	v_cvt_f32_ubyte2_e32 v84, v80
	v_cvt_f32_ubyte3_e32 v85, v80
	v_mul_f32_e32 v82, s34, v82
	v_mul_f32_e32 v83, s34, v83
	v_mul_f32_e32 v84, s34, v84
	v_mul_f32_e32 v85, s34, v85
	v_fma_f32 v100, v50, v82, v100
	v_fma_f32 v101, v51, v83, v101
	v_fma_f32 v102, v52, v84, v102
	v_fma_f32 v103, v53, v85, v103
	v_cvt_f32_ubyte0_e32 v86, v81
	v_cvt_f32_ubyte1_e32 v87, v81
	v_cvt_f32_ubyte2_e32 v88, v81
	v_cvt_f32_ubyte3_e32 v89, v81
	v_mul_f32_e32 v86, s34, v86
	v_mul_f32_e32 v87, s34, v87
	v_mul_f32_e32 v88, s34, v88
	v_mul_f32_e32 v89, s34, v89
	v_fma_f32 v96, v2, v86, v96
	v_fma_f32 v97, v3, v87, v97
	v_fma_f32 v98, v4, v88, v98
	v_fma_f32 v99, v5, v89, v99
	s_add_i32 s66, s66, 1
	s_add_u32 s6, s6, 0x100000
	s_addc_u32 s7, s7, 0
	s_cmp_eq_u32 s66, 4
	s_cbranch_scc0 .LBB0_1004
	v_lshlrev_b32_e32 v0, 1, v118
	v_lshl_add_u64 v[6:7], s[4:5], 0, v[0:1]
	v_lshlrev_b64 v[2:3], 11, v[112:113]
	v_lshl_add_u64 v[8:9], v[6:7], 0, v[2:3]
	v_cvt_pk_bf16_f32 v2, v184, v185
	v_cvt_pk_bf16_f32 v3, v186, v187
	v_cvt_pk_bf16_f32 v4, v180, v181
	v_cvt_pk_bf16_f32 v5, v182, v183
	global_store_dwordx4 v[8:9], v[2:5], off
	v_readlane_b32 s46, v254, 29
	s_mov_b32 s38, 0
	v_cvt_pk_bf16_f32 v2, v176, v177
	v_cvt_pk_bf16_f32 v3, v178, v179
	v_cvt_pk_bf16_f32 v4, v172, v173
	v_cvt_pk_bf16_f32 v5, v174, v175
	global_store_dwordx4 v[8:9], v[2:5], off offset:64
	v_readlane_b32 s47, v254, 30
	s_nop 0
	v_lshlrev_b64 v[2:3], 11, v[110:111]
	v_lshl_add_u64 v[8:9], v[6:7], 0, v[2:3]
	v_cvt_pk_bf16_f32 v2, v168, v169
	v_cvt_pk_bf16_f32 v3, v170, v171
	v_cvt_pk_bf16_f32 v4, v164, v165
	v_cvt_pk_bf16_f32 v5, v166, v167
	global_store_dwordx4 v[8:9], v[2:5], off
	s_nop 1
	v_cvt_pk_bf16_f32 v2, v160, v161
	v_cvt_pk_bf16_f32 v3, v162, v163
	v_cvt_pk_bf16_f32 v4, v156, v157
	v_cvt_pk_bf16_f32 v5, v158, v159
	global_store_dwordx4 v[8:9], v[2:5], off offset:64
	s_nop 1
	v_lshlrev_b64 v[2:3], 11, v[104:105]
	v_lshl_add_u64 v[8:9], v[6:7], 0, v[2:3]
	v_cvt_pk_bf16_f32 v2, v136, v137
	v_cvt_pk_bf16_f32 v3, v150, v151
	v_cvt_pk_bf16_f32 v4, v130, v131
	v_cvt_pk_bf16_f32 v5, v134, v135
	global_store_dwordx4 v[8:9], v[2:5], off
	s_nop 1
	v_cvt_pk_bf16_f32 v2, v124, v125
	v_cvt_pk_bf16_f32 v3, v126, v127
	v_cvt_pk_bf16_f32 v4, v120, v121
	v_cvt_pk_bf16_f32 v5, v122, v123
	global_store_dwordx4 v[8:9], v[2:5], off offset:64
	s_nop 1
	v_lshlrev_b64 v[2:3], 11, v[94:95]
	v_lshl_add_u64 v[6:7], v[6:7], 0, v[2:3]
	v_cvt_pk_bf16_f32 v2, v114, v115
	v_cvt_pk_bf16_f32 v3, v116, v117
	v_cvt_pk_bf16_f32 v4, v106, v107
	v_cvt_pk_bf16_f32 v5, v108, v109
	global_store_dwordx4 v[6:7], v[2:5], off
	s_nop 1
	v_cvt_pk_bf16_f32 v2, v100, v101
	v_cvt_pk_bf16_f32 v3, v102, v103
	v_cvt_pk_bf16_f32 v4, v96, v97
	v_cvt_pk_bf16_f32 v5, v98, v99
	global_store_dwordx4 v[6:7], v[2:5], off offset:64
